# grid barrier poll loop without s_sleep (on v028)
# speedup vs baseline: 1.0026x; 1.0026x over previous
; __global__ void __launch_bounds__(256, 2) mega(Params p, int ph_lo, int ph_hi) {
;     ...
;     if (ph + 1 < ph_hi && s != 5) grid.sync();
.Lgs_poll:
	global_load_dword v0, v2, s[10:11] sc1
	s_waitcnt vmcnt(0)
	v_readfirstlane_b32 s8, v0
	s_cmp_lg_u32 s8, s9
	s_cbranch_scc1 .Lgs_to_inv
	s_branch .Lgs_poll
